# thin_gemm<0,22> (down-proj tail rows): coalesced 64B-per-row loads + wave-private LDS re-layout into MFMA operand layout; same k-order, bit-identical
# speedup vs baseline: 1.0196x; 1.0196x over previous
.LBB0_1452:
	s_waitcnt vmcnt(0)
	s_and_b32 s20, s0, 0x3e0
	s_and_b32 s12, s1, 0xffffffe0
	v_add_u32_e32 v114, s12, v21
	v_and_b32_e32 v116, 63, v136
	v_lshrrev_b32_e32 v117, 2, v116
	v_and_b32_e32 v118, 3, v116
	v_lshrrev_b32_e32 v119, 6, v136
	v_mul_u32_u24_e32 v138, 0x2c0, v119
	v_lshl_add_u32 v240, v118, 4, v138
	v_mov_b32_e32 v241, 0
	v_add_u32_e32 v246, s12, v117
	v_add_u32_e32 v246, 0x4000, v246
	v_add_u32_e32 v247, s20, v117
	s_movk_i32 s13, 0x1600
	v_mad_u64_u32 v[238:239], vcc, v246, s76, v[240:241]
	v_mad_u64_u32 v[242:243], vcc, v247, s13, v[240:241]
	v_ashrrev_i32_e32 v115, 31, v114
	v_lshl_add_u64 v[238:239], s[6:7], 0, v[238:239]
	v_lshl_add_u64 v[242:243], s[44:45], 0, v[242:243]
	s_lshl_b32 vcc_lo, s76, 4
	s_mov_b32 vcc_hi, 0
	v_lshl_add_u64 v[240:241], v[238:239], 0, vcc
	s_mov_b32 vcc_lo, 0x16000
	v_lshrrev_b32_e32 v246, 2, v117
	v_lshl_add_u64 v[244:245], v[242:243], 0, vcc
	global_load_dwordx4 v[26:29], v[238:239], off
	global_load_dwordx4 v[30:33], v[240:241], off
	global_load_dwordx4 v[34:37], v[242:243], off
	global_load_dwordx4 v[38:41], v[244:245], off
	global_load_dwordx4 v[42:45], v[238:239], off offset:64
	global_load_dwordx4 v[46:49], v[240:241], off offset:64
	global_load_dwordx4 v[50:53], v[242:243], off offset:64
	global_load_dwordx4 v[54:57], v[244:245], off offset:64
	v_xor_b32_e32 v246, v246, v118
	v_lshlrev_b32_e32 v246, 4, v246
	v_lshl_add_u32 v246, v117, 6, v246
	v_lshl_add_u32 v246, v119, 12, v246
	v_add_u32_e32 v246, 0x8000, v246
	global_load_dwordx4 v[58:61], v[238:239], off offset:128
	global_load_dwordx4 v[62:65], v[240:241], off offset:128
	global_load_dwordx4 v[66:69], v[242:243], off offset:128
	global_load_dwordx4 v[70:73], v[244:245], off offset:128
	global_load_dwordx4 v[74:77], v[238:239], off offset:192
	global_load_dwordx4 v[78:81], v[240:241], off offset:192
	global_load_dwordx4 v[82:85], v[242:243], off offset:192
	global_load_dwordx4 v[86:89], v[244:245], off offset:192
	v_and_b32_e32 v247, 15, v20
	v_lshrrev_b32_e32 v117, 2, v247
	v_lshrrev_b32_e32 v118, 5, v116
	v_xor_b32_e32 v117, v117, v118
	v_lshlrev_b32_e32 v117, 4, v117
	v_lshl_add_u32 v117, v247, 6, v117
	v_lshrrev_b32_e32 v118, 4, v20
	v_lshl_add_u32 v117, v118, 10, v117
	v_lshl_add_u32 v117, v119, 12, v117
	v_add_u32_e32 v247, 0x8000, v117
	v_xor_b32_e32 v117, 32, v247
	global_load_dwordx4 v[90:93], v[238:239], off offset:256
	global_load_dwordx4 v[94:97], v[240:241], off offset:256
	global_load_dwordx4 v[98:101], v[242:243], off offset:256
	global_load_dwordx4 v[102:105], v[244:245], off offset:256
	global_load_dwordx4 v[106:109], v[238:239], off offset:320
	global_load_dwordx4 v[110:113], v[240:241], off offset:320
	global_load_dwordx4 v[120:123], v[242:243], off offset:320
	global_load_dwordx4 v[124:127], v[244:245], off offset:320
	global_load_dwordx4 v[128:131], v[238:239], off offset:384
	global_load_dwordx4 v[132:135], v[240:241], off offset:384
	global_load_dwordx4 v[152:155], v[242:243], off offset:384
	global_load_dwordx4 v[156:159], v[244:245], off offset:384
	global_load_dwordx4 v[160:163], v[238:239], off offset:448
	global_load_dwordx4 v[164:167], v[240:241], off offset:448
	global_load_dwordx4 v[168:171], v[242:243], off offset:448
	global_load_dwordx4 v[172:175], v[244:245], off offset:448
	global_load_dwordx4 v[190:193], v[238:239], off offset:512
	global_load_dwordx4 v[194:197], v[240:241], off offset:512
	global_load_dwordx4 v[198:201], v[242:243], off offset:512
	global_load_dwordx4 v[202:205], v[244:245], off offset:512
	global_load_dwordx4 v[206:209], v[238:239], off offset:576
	global_load_dwordx4 v[210:213], v[240:241], off offset:576
	global_load_dwordx4 v[214:217], v[242:243], off offset:576
	global_load_dwordx4 v[218:221], v[244:245], off offset:576
	global_load_dwordx4 v[222:225], v[238:239], off offset:640
	global_load_dwordx4 v[226:229], v[240:241], off offset:640
	global_load_dwordx4 v[230:233], v[242:243], off offset:640
	global_load_dwordx4 v[234:237], v[244:245], off offset:640
	s_add_i32 s1, s1, s96
	s_add_i32 s0, s0, s15
	s_cmpk_lt_i32 s1, 0x100
	s_waitcnt vmcnt(40)
	ds_write_b128 v246, v[26:29]
	ds_write_b128 v246, v[30:33] offset:1024
	ds_write_b128 v246, v[34:37] offset:2048
	ds_write_b128 v246, v[38:41] offset:3072
	s_waitcnt lgkmcnt(0)
	ds_read_b128 v[26:29], v247
	ds_read_b128 v[34:37], v247 offset:2048
	ds_read_b128 v[30:33], v117
	ds_read_b128 v[38:41], v117 offset:2048
	s_waitcnt lgkmcnt(2)
	v_mfma_f32_32x32x16_bf16 v[0:15], v[34:37], v[26:29], 0
	s_waitcnt lgkmcnt(0)
	v_mfma_f32_32x32x16_bf16 v[0:15], v[38:41], v[30:33], v[0:15]
	s_waitcnt vmcnt(36)
	ds_write_b128 v246, v[42:45]
	ds_write_b128 v246, v[46:49] offset:1024
	ds_write_b128 v246, v[50:53] offset:2048
	ds_write_b128 v246, v[54:57] offset:3072
	s_waitcnt lgkmcnt(0)
	ds_read_b128 v[42:45], v247
	ds_read_b128 v[50:53], v247 offset:2048
	ds_read_b128 v[46:49], v117
	ds_read_b128 v[54:57], v117 offset:2048
	s_waitcnt lgkmcnt(2)
	v_mfma_f32_32x32x16_bf16 v[0:15], v[50:53], v[42:45], v[0:15]
	s_waitcnt lgkmcnt(0)
	v_mfma_f32_32x32x16_bf16 v[0:15], v[54:57], v[46:49], v[0:15]
	s_waitcnt vmcnt(32)
	ds_write_b128 v246, v[58:61]
	ds_write_b128 v246, v[62:65] offset:1024
	ds_write_b128 v246, v[66:69] offset:2048
	ds_write_b128 v246, v[70:73] offset:3072
	s_waitcnt lgkmcnt(0)
	ds_read_b128 v[58:61], v247
	ds_read_b128 v[66:69], v247 offset:2048
	ds_read_b128 v[62:65], v117
	ds_read_b128 v[70:73], v117 offset:2048
	s_waitcnt lgkmcnt(2)
	v_mfma_f32_32x32x16_bf16 v[0:15], v[66:69], v[58:61], v[0:15]
	s_waitcnt lgkmcnt(0)
	v_mfma_f32_32x32x16_bf16 v[0:15], v[70:73], v[62:65], v[0:15]
	s_waitcnt vmcnt(28)
	ds_write_b128 v246, v[74:77]
	ds_write_b128 v246, v[78:81] offset:1024
	ds_write_b128 v246, v[82:85] offset:2048
	ds_write_b128 v246, v[86:89] offset:3072
	s_waitcnt lgkmcnt(0)
	ds_read_b128 v[74:77], v247
	ds_read_b128 v[82:85], v247 offset:2048
	ds_read_b128 v[78:81], v117
	ds_read_b128 v[86:89], v117 offset:2048
	s_waitcnt lgkmcnt(2)
	v_mfma_f32_32x32x16_bf16 v[0:15], v[82:85], v[74:77], v[0:15]
	s_waitcnt lgkmcnt(0)
	v_mfma_f32_32x32x16_bf16 v[0:15], v[86:89], v[78:81], v[0:15]
	s_waitcnt vmcnt(24)
	ds_write_b128 v246, v[90:93]
	ds_write_b128 v246, v[94:97] offset:1024
	ds_write_b128 v246, v[98:101] offset:2048
	ds_write_b128 v246, v[102:105] offset:3072
	s_waitcnt lgkmcnt(0)
	ds_read_b128 v[90:93], v247
	ds_read_b128 v[98:101], v247 offset:2048
	ds_read_b128 v[94:97], v117
	ds_read_b128 v[102:105], v117 offset:2048
	s_waitcnt lgkmcnt(2)
	v_mfma_f32_32x32x16_bf16 v[0:15], v[98:101], v[90:93], v[0:15]
	s_waitcnt lgkmcnt(0)
	v_mfma_f32_32x32x16_bf16 v[0:15], v[102:105], v[94:97], v[0:15]
	s_waitcnt vmcnt(20)
	ds_write_b128 v246, v[106:109]
	ds_write_b128 v246, v[110:113] offset:1024
	ds_write_b128 v246, v[120:123] offset:2048
	ds_write_b128 v246, v[124:127] offset:3072
	s_waitcnt lgkmcnt(0)
	ds_read_b128 v[106:109], v247
	ds_read_b128 v[120:123], v247 offset:2048
	ds_read_b128 v[110:113], v117
	ds_read_b128 v[124:127], v117 offset:2048
	s_waitcnt lgkmcnt(2)
	v_mfma_f32_32x32x16_bf16 v[0:15], v[120:123], v[106:109], v[0:15]
	s_waitcnt lgkmcnt(0)
	v_mfma_f32_32x32x16_bf16 v[0:15], v[124:127], v[110:113], v[0:15]
	s_waitcnt vmcnt(16)
	ds_write_b128 v246, v[128:131]
	ds_write_b128 v246, v[132:135] offset:1024
	ds_write_b128 v246, v[152:155] offset:2048
	ds_write_b128 v246, v[156:159] offset:3072
	s_waitcnt lgkmcnt(0)
	ds_read_b128 v[128:131], v247
	ds_read_b128 v[152:155], v247 offset:2048
	ds_read_b128 v[132:135], v117
	ds_read_b128 v[156:159], v117 offset:2048
	s_waitcnt lgkmcnt(2)
	v_mfma_f32_32x32x16_bf16 v[0:15], v[152:155], v[128:131], v[0:15]
	s_waitcnt lgkmcnt(0)
	v_mfma_f32_32x32x16_bf16 v[0:15], v[156:159], v[132:135], v[0:15]
	s_waitcnt vmcnt(12)
	ds_write_b128 v246, v[160:163]
	ds_write_b128 v246, v[164:167] offset:1024
	ds_write_b128 v246, v[168:171] offset:2048
	ds_write_b128 v246, v[172:175] offset:3072
	s_waitcnt lgkmcnt(0)
	ds_read_b128 v[160:163], v247
	ds_read_b128 v[168:171], v247 offset:2048
	ds_read_b128 v[164:167], v117
	ds_read_b128 v[172:175], v117 offset:2048
	s_waitcnt lgkmcnt(2)
	v_mfma_f32_32x32x16_bf16 v[0:15], v[168:171], v[160:163], v[0:15]
	s_waitcnt lgkmcnt(0)
	v_mfma_f32_32x32x16_bf16 v[0:15], v[172:175], v[164:167], v[0:15]
	s_waitcnt vmcnt(8)
	ds_write_b128 v246, v[190:193]
	ds_write_b128 v246, v[194:197] offset:1024
	ds_write_b128 v246, v[198:201] offset:2048
	ds_write_b128 v246, v[202:205] offset:3072
	s_waitcnt lgkmcnt(0)
	ds_read_b128 v[190:193], v247
	ds_read_b128 v[198:201], v247 offset:2048
	ds_read_b128 v[194:197], v117
	ds_read_b128 v[202:205], v117 offset:2048
	s_waitcnt lgkmcnt(2)
	v_mfma_f32_32x32x16_bf16 v[0:15], v[198:201], v[190:193], v[0:15]
	s_waitcnt lgkmcnt(0)
	v_mfma_f32_32x32x16_bf16 v[0:15], v[202:205], v[194:197], v[0:15]
	s_waitcnt vmcnt(4)
	ds_write_b128 v246, v[206:209]
	ds_write_b128 v246, v[210:213] offset:1024
	ds_write_b128 v246, v[214:217] offset:2048
	ds_write_b128 v246, v[218:221] offset:3072
	s_waitcnt lgkmcnt(0)
	ds_read_b128 v[206:209], v247
	ds_read_b128 v[214:217], v247 offset:2048
	ds_read_b128 v[210:213], v117
	ds_read_b128 v[218:221], v117 offset:2048
	s_waitcnt lgkmcnt(2)
	v_mfma_f32_32x32x16_bf16 v[0:15], v[214:217], v[206:209], v[0:15]
	s_waitcnt lgkmcnt(0)
	v_mfma_f32_32x32x16_bf16 v[0:15], v[218:221], v[210:213], v[0:15]
	s_waitcnt vmcnt(0)
	ds_write_b128 v246, v[222:225]
	ds_write_b128 v246, v[226:229] offset:1024
	ds_write_b128 v246, v[230:233] offset:2048
	ds_write_b128 v246, v[234:237] offset:3072
	s_waitcnt lgkmcnt(0)
	ds_read_b128 v[222:225], v247
	ds_read_b128 v[230:233], v247 offset:2048
	ds_read_b128 v[226:229], v117
	ds_read_b128 v[234:237], v117 offset:2048
	s_waitcnt lgkmcnt(2)
	v_mfma_f32_32x32x16_bf16 v[0:15], v[230:233], v[222:225], v[0:15]
	s_waitcnt lgkmcnt(0)
	v_mfma_f32_32x32x16_bf16 v[0:15], v[234:237], v[226:229], v[0:15]
	v_add_u32_e32 v30, s20, v22
	v_lshlrev_b64 v[32:33], 11, v[114:115]
	v_ashrrev_i32_e32 v31, 31, v30
	v_lshl_add_u64 v[32:33], s[4:5], 0, v[32:33]
	v_lshl_add_u64 v[30:31], v[30:31], 1, v[32:33]
	s_nop 11
	ds_write2st64_b32 v23, v0, v1 offset1:1
	ds_write2st64_b32 v23, v2, v3 offset0:2 offset1:3
	ds_write2st64_b32 v23, v4, v5 offset0:4 offset1:5
	ds_write2st64_b32 v23, v6, v7 offset0:6 offset1:7
	ds_write2st64_b32 v23, v8, v9 offset0:8 offset1:9
	ds_write2st64_b32 v23, v10, v11 offset0:10 offset1:11
	ds_write2st64_b32 v23, v12, v13 offset0:12 offset1:13
	ds_write2st64_b32 v23, v14, v15 offset0:14 offset1:15
	s_waitcnt lgkmcnt(0)
	s_barrier
	ds_read2st64_b32 v[0:1], v24 offset1:1
	ds_read2st64_b32 v[2:3], v24 offset0:16 offset1:17
	ds_read2st64_b32 v[4:5], v24 offset0:32 offset1:33
	ds_read2st64_b32 v[6:7], v24 offset0:48 offset1:49
	ds_read2st64_b32 v[8:9], v24 offset0:64 offset1:65
	ds_read2st64_b32 v[10:11], v24 offset0:80 offset1:81
	ds_read2st64_b32 v[12:13], v24 offset0:96 offset1:97
	ds_read2st64_b32 v[14:15], v24 offset0:112 offset1:113
	s_waitcnt lgkmcnt(7)
	v_add_f32_e32 v0, 0, v0
	v_add_f32_e32 v1, 0, v1
	s_waitcnt lgkmcnt(6)
	v_add_f32_e32 v0, v0, v2
	v_add_f32_e32 v1, v1, v3
	s_waitcnt lgkmcnt(5)
	v_add_f32_e32 v0, v0, v4
	v_add_f32_e32 v1, v1, v5
	s_waitcnt lgkmcnt(4)
	v_add_f32_e32 v0, v0, v6
	v_add_f32_e32 v1, v1, v7
	s_waitcnt lgkmcnt(3)
	v_add_f32_e32 v0, v0, v8
	v_add_f32_e32 v1, v1, v9
	s_waitcnt lgkmcnt(2)
	v_add_f32_e32 v0, v0, v10
	v_add_f32_e32 v1, v1, v11
	s_waitcnt lgkmcnt(1)
	v_add_f32_e32 v0, v0, v12
	v_add_f32_e32 v1, v1, v13
	s_waitcnt lgkmcnt(0)
	v_add_f32_e32 v0, v0, v14
	v_add_f32_e32 v1, v1, v15
	v_cvt_pk_bf16_f32 v0, v0, v1
	global_store_dword v[30:31], v0, off
	s_barrier
	s_cbranch_scc1 .LBB0_1452
